# tile-index decomposition in the five GEMM tile loops: division by the (always 8) group height as shift+mask instead of float-reciprocal division
# baseline (speedup 1.0000x reference)
.LBB0_167:
	s_add_i32 s71, s71, 1
	s_mul_i32 s3, s71, s69
	s_mul_hi_u32 s12, s71, s14
	s_add_i32 s3, s12, s3
	s_mul_i32 s12, s71, s14
	s_add_u32 s12, s12, s15
	s_addc_u32 s13, s3, s70
	v_mov_b64_e32 v[2:3], 0xd00
	v_cmp_lt_i64_e64 s[40:41], s[12:13], v[2:3]
	v_mov_b64_e32 v[2:3], 0xcff
	v_cmp_gt_i64_e32 vcc, s[12:13], v[2:3]
	s_cbranch_vccnz .LBB0_169
	s_ashr_i32 s3, s12, 31
	s_lshr_b32 s3, s3, 29
	s_add_i32 s3, s12, s3
	s_ashr_i32 s13, s3, 3
	s_and_b32 s3, s3, -8
	s_sub_i32 s3, s12, s3
	s_cmp_lt_i32 s3, 0
	s_movk_i32 s12, 0x1a1
	s_cselect_b32 s12, s12, 0x1a0
	s_mul_i32 s3, s3, s12
	s_add_i32 s3, s3, s13
	s_mul_hi_i32 s12, s3, 0x4ec4ec4f
	s_lshr_b32 s13, s12, 31
	s_ashr_i32 s12, s12, 6
	s_add_i32 s12, s12, s13
	s_lshl_b32 s13, s12, 3
	s_sub_i32 s24, 0x80, s13
	s_min_i32 s24, s24, 8
	s_mulk_i32 s12, 0xd0
	s_sub_i32 s3, s3, s12
	s_ashr_i32 s48, s3, 3
	s_and_b32 s3, s3, 7
	s_add_i32 s50, s13, s3

.LBB0_544:
	s_ashr_i32 s14, s24, 3
	s_add_i32 s14, s26, s14
	s_ashr_i32 s15, s14, 31
	s_lshr_b32 s15, s15, 27
	s_add_i32 s15, s14, s15
	s_ashr_i32 s24, s15, 5
	s_lshl_b32 s24, s24, 3
	s_sub_i32 s25, 0x80, s24
	s_min_i32 s25, s25, 8
	s_andn2_b32 s15, s15, 31
	s_sub_i32 s14, s14, s15
	s_ashr_i32 s44, s14, 3
	s_and_b32 s14, s14, 7
	s_add_i32 s46, s24, s14

.LBB0_638:
	s_ashr_i32 s11, s11, 3
	s_add_i32 s11, s25, s11
	s_ashr_i32 s14, s11, 31
	s_lshr_b32 s14, s14, 27
	s_add_i32 s14, s11, s14
	s_ashr_i32 s15, s14, 5
	s_lshl_b32 s15, s15, 3
	s_sub_i32 s24, 0x100, s15
	s_min_i32 s24, s24, 8
	s_andn2_b32 s14, s14, 31
	s_sub_i32 s11, s11, s14
	s_ashr_i32 s46, s11, 3
	s_and_b32 s11, s11, 7
	s_add_i32 s48, s15, s11

.LBB0_741:
	s_add_i32 s33, s33, 1
	s_mul_i32 s11, s33, s92
	s_mul_hi_u32 s14, s33, s18
	s_add_i32 s11, s14, s11
	s_mul_i32 s14, s33, s18
	s_add_u32 s14, s14, s19
	s_addc_u32 s15, s11, s2
	v_cmp_gt_i64_e32 vcc, s[14:15], v[190:191]
	v_cmp_lt_i64_e64 s[44:45], s[14:15], v[188:189]
	s_cbranch_vccnz .LBB0_743
	s_ashr_i32 s11, s14, 31
	s_lshr_b32 s11, s11, 29
	s_add_i32 s11, s14, s11
	s_ashr_i32 s15, s11, 3
	s_and_b32 s11, s11, -8
	s_sub_i32 s11, s14, s11
	s_cmp_lt_i32 s11, 0
	s_movk_i32 s14, 0x2c1
	s_cselect_b32 s14, s14, 0x2c0
	s_mul_i32 s11, s11, s14
	s_add_i32 s11, s11, s15
	s_mul_hi_i32 s14, s11, 0x2e8ba2e9
	s_lshr_b32 s15, s14, 31
	s_ashr_i32 s14, s14, 5
	s_add_i32 s14, s14, s15
	s_lshl_b32 s15, s14, 3
	s_sub_i32 s16, 0x100, s15
	s_min_i32 s16, s16, 8
	s_mulk_i32 s14, 0xb0
	s_sub_i32 s11, s11, s14
	s_ashr_i32 s74, s11, 3
	s_and_b32 s11, s11, 7
	s_add_i32 s80, s15, s11

.LBB0_949:
	s_ashr_i32 s8, s10, 3
	s_add_i32 s8, s13, s8
	s_ashr_i32 s9, s8, 31
	s_lshr_b32 s9, s9, 27
	s_add_i32 s9, s8, s9
	s_ashr_i32 s10, s9, 5
	s_lshl_b32 s10, s10, 3
	s_sub_i32 s11, 0x100, s10
	s_min_i32 s11, s11, 8
	s_andn2_b32 s9, s9, 31
	s_sub_i32 s8, s8, s9
	s_ashr_i32 s29, s8, 3
	s_and_b32 s8, s8, 7
	s_add_i32 s56, s10, s8
